# SWA attention: a workgroup runs the 4 query heads of one KV head on one query block back to back, K/V staged once per group
# baseline (speedup 1.0000x reference)
.LBB0_377:
	s_or_b64 exec, exec, s[4:5]
	v_readlane_b32 s8, v246, 40
	v_readlane_b32 s9, v246, 41
	s_mov_b64 s[4:5], 0
	s_andn2_b64 vcc, exec, s[8:9]
	s_waitcnt lgkmcnt(0)
	s_barrier
	s_cbranch_vccnz .LBB0_401
	s_add_u32 s4, s50, s4
	s_addc_u32 s5, s51, s5
	s_add_u32 s60, s4, 0xd100000
	s_addc_u32 s61, s5, 0
	s_add_u32 s72, s4, 0x10100000
	s_addc_u32 s73, s5, 0
	s_add_u32 s74, s4, 0x13100000
	s_addc_u32 s75, s5, 0
	s_add_u32 s76, s4, 0x15100000
	s_addc_u32 s77, s5, 0
	s_lshl_b32 s86, s40, 4
	s_mov_b32 s87, s2
	s_mov_b32 s32, 0
	s_cmpk_lg_i32 s30, 0x100
	s_cbranch_scc1 .Lw3_nogroup
	s_mov_b32 s32, 1
	s_lshr_b32 s87, s2, 2
	s_lshl_b32 s87, s87, 4
	s_and_b32 s4, s2, 3
	s_lshl_b32 s4, s4, 2
	s_or_b32 s87, s87, s4

.LBB0_379:
.LBB0_380:
	v_add_u32_e32 v172, v103, v124
	ds_read_b128 v[140:143], v172
	ds_read_b128 v[144:147], v172 offset:2560
	ds_read_b128 v[148:151], v172 offset:5120
	ds_read_b128 v[152:155], v172 offset:7680
	s_waitcnt lgkmcnt(3)
	v_mfma_f32_16x16x32_bf16 v[2:5], v[140:143], v[74:77], v[2:5]
	v_mfma_f32_16x16x32_bf16 v[6:9], v[140:143], v[78:81], v[6:9]
	s_waitcnt lgkmcnt(2)
	v_mfma_f32_16x16x32_bf16 v[10:13], v[144:147], v[74:77], v[10:13]
	v_mfma_f32_16x16x32_bf16 v[14:17], v[144:147], v[78:81], v[14:17]
	s_waitcnt lgkmcnt(1)
	v_mfma_f32_16x16x32_bf16 v[18:21], v[148:151], v[74:77], v[18:21]
	v_mfma_f32_16x16x32_bf16 v[22:25], v[148:151], v[78:81], v[22:25]
	s_waitcnt lgkmcnt(0)
	v_mfma_f32_16x16x32_bf16 v[26:29], v[152:155], v[74:77], v[26:29]
	v_mfma_f32_16x16x32_bf16 v[30:33], v[152:155], v[78:81], v[30:33]
	ds_bpermute_b32 v166, v126, v87
	ds_bpermute_b32 v167, v126, v136
	s_waitcnt lgkmcnt(0)
	v_add_f32_e32 v87, v87, v166
	v_add_f32_e32 v136, v136, v167
	ds_bpermute_b32 v166, v85, v87
	ds_bpermute_b32 v167, v85, v136
	s_waitcnt lgkmcnt(0)
	v_add_f32_e32 v87, v87, v166
	v_add_f32_e32 v136, v136, v167
	s_barrier
	v_div_scale_f32 v34, s[8:9], v87, v87, 1.0
	v_rcp_f32_e32 v35, v34
	s_nop 0
	v_fma_f32 v36, -v34, v35, 1.0
	v_fmac_f32_e32 v35, v36, v35
	v_div_scale_f32 v36, vcc, 1.0, v87, 1.0
	v_mul_f32_e32 v37, v36, v35
	v_fma_f32 v38, -v34, v37, v36
	v_fmac_f32_e32 v37, v38, v35
	v_fma_f32 v34, -v34, v37, v36
	v_div_fmas_f32 v34, v34, v35, v37
	v_div_fixup_f32 v34, v34, v87, 1.0
	v_div_scale_f32 v42, s[8:9], v136, v136, 1.0
	v_rcp_f32_e32 v43, v42
	s_nop 0
	v_fma_f32 v44, -v42, v43, 1.0
	v_fmac_f32_e32 v43, v44, v43
	v_div_scale_f32 v44, vcc, 1.0, v136, 1.0
	v_mul_f32_e32 v45, v44, v43
	v_fma_f32 v46, -v42, v45, v44
	v_fmac_f32_e32 v45, v46, v43
	v_fma_f32 v42, -v42, v45, v44
	v_div_fmas_f32 v42, v42, v43, v45
	v_div_fixup_f32 v42, v42, v136, 1.0
	s_lshl_b32 s4, s88, 7
	s_add_u32 s4, s76, s4
	s_addc_u32 s5, s77, 0
	v_and_b32_e32 v138, 15, v162
	v_add_u32_e32 v138, v93, v138
	v_ashrrev_i32_e32 v139, 31, v138
	v_lshlrev_b64 v[138:139], 11, v[138:139]
	v_lshl_add_u64 v[138:139], s[4:5], 0, v[138:139]
	v_bfe_u32 v166, v162, 4, 2
	v_lshlrev_b32_e32 v166, 3, v166
	v_mov_b32_e32 v167, 0
	v_lshl_add_u64 v[138:139], v[138:139], 0, v[166:167]
	v_add_co_u32_e32 v166, vcc, 0x8000, v138
	s_nop 1
	v_addc_co_u32_e32 v167, vcc, 0, v139, vcc
	v_mul_f32_e32 v2, v2, v34
	v_mul_f32_e32 v3, v3, v34
	v_mul_f32_e32 v4, v4, v34
	v_mul_f32_e32 v5, v5, v34
	v_cvt_pk_bf16_f32 v168, v2, v3
	v_cvt_pk_bf16_f32 v169, v4, v5
	global_store_dwordx2 v[138:139], v[168:169], off
	v_mul_f32_e32 v6, v6, v42
	v_mul_f32_e32 v7, v7, v42
	v_mul_f32_e32 v8, v8, v42
	v_mul_f32_e32 v9, v9, v42
	v_cvt_pk_bf16_f32 v170, v6, v7
	v_cvt_pk_bf16_f32 v171, v8, v9
	global_store_dwordx2 v[166:167], v[170:171], off
	v_mul_f32_e32 v10, v10, v34
	v_mul_f32_e32 v11, v11, v34
	v_mul_f32_e32 v12, v12, v34
	v_mul_f32_e32 v13, v13, v34
	v_cvt_pk_bf16_f32 v168, v10, v11
	v_cvt_pk_bf16_f32 v169, v12, v13
	global_store_dwordx2 v[138:139], v[168:169], off offset:32
	v_mul_f32_e32 v14, v14, v42
	v_mul_f32_e32 v15, v15, v42
	v_mul_f32_e32 v16, v16, v42
	v_mul_f32_e32 v17, v17, v42
	v_cvt_pk_bf16_f32 v170, v14, v15
	v_cvt_pk_bf16_f32 v171, v16, v17
	global_store_dwordx2 v[166:167], v[170:171], off offset:32
	v_mul_f32_e32 v18, v18, v34
	v_mul_f32_e32 v19, v19, v34
	v_mul_f32_e32 v20, v20, v34
	v_mul_f32_e32 v21, v21, v34
	v_cvt_pk_bf16_f32 v168, v18, v19
	v_cvt_pk_bf16_f32 v169, v20, v21
	global_store_dwordx2 v[138:139], v[168:169], off offset:64
	v_mul_f32_e32 v22, v22, v42
	v_mul_f32_e32 v23, v23, v42
	v_mul_f32_e32 v24, v24, v42
	v_mul_f32_e32 v25, v25, v42
	v_cvt_pk_bf16_f32 v170, v22, v23
	v_cvt_pk_bf16_f32 v171, v24, v25
	global_store_dwordx2 v[166:167], v[170:171], off offset:64
	v_mul_f32_e32 v26, v26, v34
	v_mul_f32_e32 v27, v27, v34
	v_mul_f32_e32 v28, v28, v34
	v_mul_f32_e32 v29, v29, v34
	v_cvt_pk_bf16_f32 v168, v26, v27
	v_cvt_pk_bf16_f32 v169, v28, v29
	global_store_dwordx2 v[138:139], v[168:169], off offset:96
	v_mul_f32_e32 v30, v30, v42
	v_mul_f32_e32 v31, v31, v42
	v_mul_f32_e32 v32, v32, v42
	v_mul_f32_e32 v33, v33, v42
	v_cvt_pk_bf16_f32 v170, v30, v31
	v_cvt_pk_bf16_f32 v171, v32, v33
	global_store_dwordx2 v[166:167], v[170:171], off offset:96
	s_cmp_eq_u32 s32, 0
	s_cbranch_scc1 .Lw3_oldstep
	s_add_i32 s87, s87, 1
	s_and_b32 s4, s87, 3
	s_cmp_eq_u32 s4, 0
	s_branch .Lw3_stepdone
.Lw3_oldstep:
	s_add_i32 s87, s87, s30
	s_cmpk_gt_i32 s87, 0x3ff
.Lw3_stepdone:
	s_cbranch_scc1 .LBB0_401
.LBB0_381:
	s_ashr_i32 s4, s87, 4
	s_lshl_b32 s9, s4, 8
	s_and_b32 s88, s87, 15
	s_add_i32 s5, s9, 0xffffff80
	s_cmp_gt_i32 s4, 0
	s_cselect_b32 s8, s5, 0
	s_lshl_b32 s4, s88, 7
	s_add_u32 s58, s60, s4
	s_addc_u32 s59, s61, 0
	s_lshl_b32 s4, s87, 19
	s_and_b32 s10, s4, 0x600000
	s_add_u32 s4, s72, s10
	s_addc_u32 s5, s73, 0
	s_add_u32 s10, s74, s10
	v_readlane_b32 s12, v246, 0
	s_addc_u32 s11, s75, 0
	s_or_b32 s54, s88, s86
	v_readlane_b32 s16, v246, 4
	v_readlane_b32 s17, v246, 5
	v_readlane_b32 s20, v246, 8
	v_readlane_b32 s21, v246, 9
	s_lshl_b64 s[80:81], s[54:55], 2
	s_mov_b64 s[16:17], s[20:21]
	s_add_u32 s80, s16, s80
	s_addc_u32 s81, s17, s81
	v_mov_b32_e32 v6, v162
	global_load_dword v14, v1, s[80:81]
	s_sub_i32 s80, s9, s8
	v_ashrrev_i32_e32 v0, 1, v6
	v_and_b32_e32 v0, 0xffffffe0, v0
	v_and_b32_e32 v13, 31, v6
	v_add_u32_e32 v93, s9, v0
	v_or_b32_e32 v86, v93, v13
	v_ashrrev_i32_e32 v87, 31, v86
	v_lshlrev_b64 v[82:83], 11, v[86:87]
	s_mov_b32 s9, s55
	v_bfe_u32 v12, v6, 5, 1
	v_lshl_add_u64 v[2:3], s[58:59], 0, v[82:83]
	v_and_b32_e32 v120, 15, v6
	v_bfe_u32 v121, v6, 4, 2
	v_add_u32_e32 v122, v93, v120
	v_ashrrev_i32_e32 v123, 31, v122
	v_lshlrev_b64 v[116:117], 11, v[122:123]
	v_lshl_add_u64 v[116:117], s[58:59], 0, v[116:117]
	v_lshlrev_b32_e32 v120, 4, v121
	v_mov_b32_e32 v121, 0
	v_lshl_add_u64 v[116:117], v[116:117], 0, v[120:121]
	v_add_co_u32_e32 v118, vcc, 0x8000, v116
	s_nop 1
	v_addc_co_u32_e32 v119, vcc, 0, v117, vcc
	s_addk_i32 s80, 0x100
	s_lshl_b64 s[58:59], s[8:9], 7
	v_lshlrev_b32_e32 v0, 4, v12
	s_add_u32 s58, s4, s58
	v_ashrrev_i32_e32 v7, 31, v6
	v_lshl_add_u64 v[16:17], v[2:3], 0, v[0:1]
	s_addc_u32 s59, s5, s59
	v_lshlrev_b64 v[2:3], 4, v[6:7]
	v_lshl_add_u64 v[4:5], s[58:59], 0, v[2:3]
	global_load_dwordx4 v[50:53], v[116:117], off
	global_load_dwordx4 v[54:57], v[116:117], off offset:64
	global_load_dwordx4 v[58:61], v[118:119], off
	v_lshrrev_b32_e32 v4, 29, v7
	v_add_u32_e32 v7, v6, v4
	s_lshl_b64 s[58:59], s[8:9], 1
	v_ashrrev_i32_e32 v18, 3, v7
	v_and_b32_e32 v7, -8, v7
	s_add_u32 s58, s10, s58
	v_ashrrev_i32_e32 v19, 31, v18
	v_sub_u32_e32 v7, v6, v7
	s_addc_u32 s59, s11, s59
	v_lshlrev_b64 v[4:5], 15, v[18:19]
	v_lshlrev_b32_e32 v8, 3, v7
	v_lshl_add_u64 v[10:11], s[58:59], 0, v[4:5]
	v_ashrrev_i32_e32 v9, 31, v8
	v_lshl_add_u64 v[10:11], v[8:9], 1, v[10:11]
	global_load_dwordx4 v[66:69], v[118:119], off offset:64
	v_readlane_b32 s13, v246, 1
	v_readlane_b32 s14, v246, 2
	v_readlane_b32 s15, v246, 3
	v_readlane_b32 s18, v246, 6
	v_readlane_b32 s19, v246, 7
	v_readlane_b32 s22, v246, 10
	v_readlane_b32 s23, v246, 11
	v_readlane_b32 s24, v246, 12
	v_readlane_b32 s25, v246, 13
	v_readlane_b32 s26, v246, 14
	v_readlane_b32 s27, v246, 15
	s_and_b32 s12, s87, 3
	s_cmp_lg_u32 s12, 0
	s_cselect_b32 s12, s32, 0
	s_cmp_lg_u32 s12, 0
	s_cbranch_scc1 .Lw3_dma_none
	v_readfirstlane_b32 s12, v162
	s_lshl_b32 s14, s8, 7
	s_lshr_b32 s12, s12, 6
	s_add_u32 s14, s4, s14
	s_addc_u32 s15, s5, 0
	s_lshl_b32 s16, s8, 1
	s_add_u32 s16, s10, s16
	s_addc_u32 s17, s11, 0
	s_add_i32 s18, s12, 0
	s_mul_i32 s19, s18, 205
	s_lshr_b32 s19, s19, 11
	s_mul_i32 s20, s19, 10
	s_sub_i32 s20, s18, s20
	v_and_b32_e32 v191, 63, v162
	v_lshl_add_u32 v191, s20, 6, v191
	v_mul_u32_u24_e32 v192, 0xcd, v191
	v_lshrrev_b32_e32 v192, 11, v192
	v_mul_u32_u24_e32 v193, 10, v192
	v_sub_u32_e32 v191, v191, v193
	v_min_u32_e32 v191, 7, v191
	s_movk_i32 s21, 0x80
	s_movk_i32 s22, 0x2000
	s_bitcmp1_b32 s19, 1
	s_cselect_b32 s21, 0x8000, s21
	s_cselect_b32 s22, 0x80, s22
	s_bitcmp1_b32 s19, 0
	s_cselect_b32 s22, s22, 0
	v_mul_u32_u24_e32 v192, s21, v192
	v_lshl_add_u32 v192, v191, 4, v192
	v_add_u32_e32 v186, s22, v192
	s_add_i32 s18, s12, 8
	s_mul_i32 s19, s18, 205
	s_lshr_b32 s19, s19, 11
	s_mul_i32 s20, s19, 10
	s_sub_i32 s20, s18, s20
	v_and_b32_e32 v191, 63, v162
	v_lshl_add_u32 v191, s20, 6, v191
	v_mul_u32_u24_e32 v192, 0xcd, v191
	v_lshrrev_b32_e32 v192, 11, v192
	v_mul_u32_u24_e32 v193, 10, v192
	v_sub_u32_e32 v191, v191, v193
	v_min_u32_e32 v191, 7, v191
	s_movk_i32 s21, 0x80
	s_movk_i32 s22, 0x2000
	s_bitcmp1_b32 s19, 1
	s_cselect_b32 s21, 0x8000, s21
	s_cselect_b32 s22, 0x80, s22
	s_bitcmp1_b32 s19, 0
	s_cselect_b32 s22, s22, 0
	v_mul_u32_u24_e32 v192, s21, v192
	v_lshl_add_u32 v192, v191, 4, v192
	v_add_u32_e32 v187, s22, v192
	s_add_i32 s18, s12, 16
	s_mul_i32 s19, s18, 205
	s_lshr_b32 s19, s19, 11
	s_mul_i32 s20, s19, 10
	s_sub_i32 s20, s18, s20
	v_and_b32_e32 v191, 63, v162
	v_lshl_add_u32 v191, s20, 6, v191
	v_mul_u32_u24_e32 v192, 0xcd, v191
	v_lshrrev_b32_e32 v192, 11, v192
	v_mul_u32_u24_e32 v193, 10, v192
	v_sub_u32_e32 v191, v191, v193
	v_min_u32_e32 v191, 7, v191
	s_movk_i32 s21, 0x80
	s_movk_i32 s22, 0x2000
	s_bitcmp1_b32 s19, 1
	s_cselect_b32 s21, 0x8000, s21
	s_cselect_b32 s22, 0x80, s22
	s_bitcmp1_b32 s19, 0
	s_cselect_b32 s22, s22, 0
	v_mul_u32_u24_e32 v192, s21, v192
	v_lshl_add_u32 v192, v191, 4, v192
	v_add_u32_e32 v188, s22, v192
	s_add_i32 s18, s12, 24
	s_mul_i32 s19, s18, 205
	s_lshr_b32 s19, s19, 11
	s_mul_i32 s20, s19, 10
	s_sub_i32 s20, s18, s20
	v_and_b32_e32 v191, 63, v162
	v_lshl_add_u32 v191, s20, 6, v191
	v_mul_u32_u24_e32 v192, 0xcd, v191
	v_lshrrev_b32_e32 v192, 11, v192
	v_mul_u32_u24_e32 v193, 10, v192
	v_sub_u32_e32 v191, v191, v193
	v_min_u32_e32 v191, 7, v191
	s_movk_i32 s21, 0x80
	s_movk_i32 s22, 0x2000
	s_bitcmp1_b32 s19, 1
	s_cselect_b32 s21, 0x8000, s21
	s_cselect_b32 s22, 0x80, s22
	s_bitcmp1_b32 s19, 0
	s_cselect_b32 s22, s22, 0
	v_mul_u32_u24_e32 v192, s21, v192
	v_lshl_add_u32 v192, v191, 4, v192
	v_add_u32_e32 v189, s22, v192
	s_add_i32 s18, s12, 32
	s_mul_i32 s19, s18, 205
	s_lshr_b32 s19, s19, 11
	s_mul_i32 s20, s19, 10
	s_sub_i32 s20, s18, s20
	v_and_b32_e32 v191, 63, v162
	v_lshl_add_u32 v191, s20, 6, v191
	v_mul_u32_u24_e32 v192, 0xcd, v191
	v_lshrrev_b32_e32 v192, 11, v192
	v_mul_u32_u24_e32 v193, 10, v192
	v_sub_u32_e32 v191, v191, v193
	v_min_u32_e32 v191, 7, v191
	s_movk_i32 s21, 0x80
	s_movk_i32 s22, 0x2000
	s_bitcmp1_b32 s19, 1
	s_cselect_b32 s21, 0x8000, s21
	s_cselect_b32 s22, 0x80, s22
	s_bitcmp1_b32 s19, 0
	s_cselect_b32 s22, s22, 0
	v_mul_u32_u24_e32 v192, s21, v192
	v_lshl_add_u32 v192, v191, 4, v192
	v_add_u32_e32 v190, s22, v192
	s_add_i32 s18, s12, 0
	s_mul_i32 s19, s18, 205
	s_lshr_b32 s19, s19, 11
	s_lshl_b32 s24, s18, 10
	s_add_u32 m0, s24, 0x400
	s_mov_b32 s25, 0x0
	s_bitcmp1_b32 s19, 1
	s_cselect_b32 s26, s16, s14
	s_cselect_b32 s27, s17, s15
	s_cselect_b32 s25, 0x0, s25
	s_add_u32 s26, s26, s25
	s_addc_u32 s27, s27, 0
	global_load_lds_dwordx4 v186, s[26:27]
	s_add_i32 s18, s12, 8
	s_mul_i32 s19, s18, 205
	s_lshr_b32 s19, s19, 11
	s_lshl_b32 s24, s18, 10
	s_add_u32 m0, s24, 0x400
	s_mov_b32 s25, 0x0
	s_bitcmp1_b32 s19, 1
	s_cselect_b32 s26, s16, s14
	s_cselect_b32 s27, s17, s15
	s_cselect_b32 s25, 0x0, s25
	s_add_u32 s26, s26, s25
	s_addc_u32 s27, s27, 0
	global_load_lds_dwordx4 v187, s[26:27]
	s_add_i32 s18, s12, 16
	s_mul_i32 s19, s18, 205
	s_lshr_b32 s19, s19, 11
	s_lshl_b32 s24, s18, 10
	s_add_u32 m0, s24, 0x400
	s_mov_b32 s25, 0x0
	s_bitcmp1_b32 s19, 1
	s_cselect_b32 s26, s16, s14
	s_cselect_b32 s27, s17, s15
	s_cselect_b32 s25, 0x0, s25
	s_add_u32 s26, s26, s25
	s_addc_u32 s27, s27, 0
	global_load_lds_dwordx4 v188, s[26:27]
	s_add_i32 s18, s12, 24
	s_mul_i32 s19, s18, 205
	s_lshr_b32 s19, s19, 11
	s_lshl_b32 s24, s18, 10
	s_add_u32 m0, s24, 0x400
	s_mov_b32 s25, 0x0
	s_bitcmp1_b32 s19, 1
	s_cselect_b32 s26, s16, s14
	s_cselect_b32 s27, s17, s15
	s_cselect_b32 s25, 0x0, s25
	s_add_u32 s26, s26, s25
	s_addc_u32 s27, s27, 0
	global_load_lds_dwordx4 v189, s[26:27]
	s_add_i32 s18, s12, 32
	s_mul_i32 s19, s18, 205
	s_lshr_b32 s19, s19, 11
	s_lshl_b32 s24, s18, 10
	s_add_u32 m0, s24, 0x400
	s_mov_b32 s25, 0x0
	s_bitcmp1_b32 s19, 1
	s_cselect_b32 s26, s16, s14
	s_cselect_b32 s27, s17, s15
	s_cselect_b32 s25, 0x0, s25
	s_add_u32 s26, s26, s25
	s_addc_u32 s27, s27, 0
	global_load_lds_dwordx4 v190, s[26:27]
	s_add_i32 s18, s12, 0
	s_mul_i32 s19, s18, 205
	s_lshr_b32 s19, s19, 11
	s_lshl_b32 s24, s18, 10
	s_add_u32 m0, s24, 0xa400
	s_mov_b32 s25, 0x4000
	s_bitcmp1_b32 s19, 1
	s_cselect_b32 s26, s16, s14
	s_cselect_b32 s27, s17, s15
	s_cselect_b32 s25, 0x100, s25
	s_add_u32 s26, s26, s25
	s_addc_u32 s27, s27, 0
	global_load_lds_dwordx4 v186, s[26:27]
	s_add_i32 s18, s12, 8
	s_mul_i32 s19, s18, 205
	s_lshr_b32 s19, s19, 11
	s_lshl_b32 s24, s18, 10
	s_add_u32 m0, s24, 0xa400
	s_mov_b32 s25, 0x4000
	s_bitcmp1_b32 s19, 1
	s_cselect_b32 s26, s16, s14
	s_cselect_b32 s27, s17, s15
	s_cselect_b32 s25, 0x100, s25
	s_add_u32 s26, s26, s25
	s_addc_u32 s27, s27, 0
	global_load_lds_dwordx4 v187, s[26:27]
	s_add_i32 s18, s12, 16
	s_mul_i32 s19, s18, 205
	s_lshr_b32 s19, s19, 11
	s_lshl_b32 s24, s18, 10
	s_add_u32 m0, s24, 0xa400
	s_mov_b32 s25, 0x4000
	s_bitcmp1_b32 s19, 1
	s_cselect_b32 s26, s16, s14
	s_cselect_b32 s27, s17, s15
	s_cselect_b32 s25, 0x100, s25
	s_add_u32 s26, s26, s25
	s_addc_u32 s27, s27, 0
	global_load_lds_dwordx4 v188, s[26:27]
	s_add_i32 s18, s12, 24
	s_mul_i32 s19, s18, 205
	s_lshr_b32 s19, s19, 11
	s_lshl_b32 s24, s18, 10
	s_add_u32 m0, s24, 0xa400
	s_mov_b32 s25, 0x4000
	s_bitcmp1_b32 s19, 1
	s_cselect_b32 s26, s16, s14
	s_cselect_b32 s27, s17, s15
	s_cselect_b32 s25, 0x100, s25
	s_add_u32 s26, s26, s25
	s_addc_u32 s27, s27, 0
	global_load_lds_dwordx4 v189, s[26:27]
	s_add_i32 s18, s12, 32
	s_mul_i32 s19, s18, 205
	s_lshr_b32 s19, s19, 11
	s_lshl_b32 s24, s18, 10
	s_add_u32 m0, s24, 0xa400
	s_mov_b32 s25, 0x4000
	s_bitcmp1_b32 s19, 1
	s_cselect_b32 s26, s16, s14
	s_cselect_b32 s27, s17, s15
	s_cselect_b32 s25, 0x100, s25
	s_add_u32 s26, s26, s25
	s_addc_u32 s27, s27, 0
	global_load_lds_dwordx4 v190, s[26:27]
	s_cmpk_lt_i32 s80, 0x180
	s_cbranch_scc1 .Lw3_dma_2pairs
	s_add_i32 s18, s12, 0
	s_mul_i32 s19, s18, 205
	s_lshr_b32 s19, s19, 11
	s_lshl_b32 s24, s18, 10
	s_add_u32 m0, s24, 0x14400
	s_mov_b32 s25, 0x8000
	s_bitcmp1_b32 s19, 1
	s_cselect_b32 s26, s16, s14
	s_cselect_b32 s27, s17, s15
	s_cselect_b32 s25, 0x200, s25
	s_add_u32 s26, s26, s25
	s_addc_u32 s27, s27, 0
	global_load_lds_dwordx4 v186, s[26:27]
	s_add_i32 s18, s12, 8
	s_mul_i32 s19, s18, 205
	s_lshr_b32 s19, s19, 11
	s_lshl_b32 s24, s18, 10
	s_add_u32 m0, s24, 0x14400
	s_mov_b32 s25, 0x8000
	s_bitcmp1_b32 s19, 1
	s_cselect_b32 s26, s16, s14
	s_cselect_b32 s27, s17, s15
	s_cselect_b32 s25, 0x200, s25
	s_add_u32 s26, s26, s25
	s_addc_u32 s27, s27, 0
	global_load_lds_dwordx4 v187, s[26:27]
	s_add_i32 s18, s12, 16
	s_mul_i32 s19, s18, 205
	s_lshr_b32 s19, s19, 11
	s_lshl_b32 s24, s18, 10
	s_add_u32 m0, s24, 0x14400
	s_mov_b32 s25, 0x8000
	s_bitcmp1_b32 s19, 1
	s_cselect_b32 s26, s16, s14
	s_cselect_b32 s27, s17, s15
	s_cselect_b32 s25, 0x200, s25
	s_add_u32 s26, s26, s25
	s_addc_u32 s27, s27, 0
	global_load_lds_dwordx4 v188, s[26:27]
	s_add_i32 s18, s12, 24
	s_mul_i32 s19, s18, 205
	s_lshr_b32 s19, s19, 11
	s_lshl_b32 s24, s18, 10
	s_add_u32 m0, s24, 0x14400
	s_mov_b32 s25, 0x8000
	s_bitcmp1_b32 s19, 1
	s_cselect_b32 s26, s16, s14
	s_cselect_b32 s27, s17, s15
	s_cselect_b32 s25, 0x200, s25
	s_add_u32 s26, s26, s25
	s_addc_u32 s27, s27, 0
	global_load_lds_dwordx4 v189, s[26:27]
	s_add_i32 s18, s12, 32
	s_mul_i32 s19, s18, 205
	s_lshr_b32 s19, s19, 11
	s_lshl_b32 s24, s18, 10
	s_add_u32 m0, s24, 0x14400
	s_mov_b32 s25, 0x8000
	s_bitcmp1_b32 s19, 1
	s_cselect_b32 s26, s16, s14
	s_cselect_b32 s27, s17, s15
	s_cselect_b32 s25, 0x200, s25
	s_add_u32 s26, s26, s25
	s_addc_u32 s27, s27, 0
	global_load_lds_dwordx4 v190, s[26:27]
	s_waitcnt vmcnt(15)
	s_branch .Lw3_dma_done
.Lw3_dma_2pairs:
	s_waitcnt vmcnt(10)
	s_branch .Lw3_dma_done
.Lw3_dma_none:
	s_waitcnt vmcnt(0)
.Lw3_dma_done:
.LBB0_383:
	v_and_b32_e32 v6, 63, v6
	v_cmp_gt_u32_e32 vcc, 32, v6
	s_cmp_gt_i32 s80, 63
	s_mov_b64 s[58:59], -1
	s_waitcnt lgkmcnt(0)
	s_barrier
	s_cbranch_scc1 .LBB0_385
	v_lshlrev_b32_e32 v7, 2, v6
	v_lshlrev_b32_e32 v35, 4, v12
	v_mul_u32_u24_e32 v92, 0x90, v13
	v_xor_b32_e32 v85, 0x80, v7
	v_lshlrev_b32_e32 v84, 2, v12
	v_mad_u32_u24 v34, v13, s49, v183
	s_mov_b64 s[58:59], 0
